# v14 + P6 attention load pipelining: V loads issued after first QK MFMA, next-tile K loads issued after last QK MFMA (loop and diagonal tile)
# baseline (speedup 1.0000x reference)
; __device__ __forceinline__ int crow(int r, int hi) { return (r & 3) + 8 * (r >> 2) + 4 * hi; }
; #define MFMA32(a, b, c) __builtin_amdgcn_mfma_f32_32x32x16_bf16((a), (b), (c), 0, 0, 0)
; __device__ __forceinline__ void sb_unit(LAS unsigned char* vs, const bf16* P, bf16* YB, int hd, int qb, int lane) {
;     ...
;     const bf16* kbase = P + (size_t)tl * NP + PC_SK + hd * HD + 8 * hh;
;     const bf16* vbase = P + (size_t)(lane >> 4) * NP + PC_SV + hd * HD + (lane & 15) * 8;
;     bf16x8 kf[8];
; #pragma unroll
;     for (int ks = 0; ks < 8; ++ks) kf[ks] = *(const bf16x8*)(kbase + (size_t)(32 * qb) * NP + 16 * ks);
;     ...
;         const int s0 = 32 * kt, sn = kt > 0 ? s0 - 32 : s0;
;         bf16x8 kn[8]; u32x4 vr[8];
; #pragma unroll
;         for (int i = 0; i < 8; ++i) vr[i] = *(const u32x4*)(vbase + (size_t)(s0 + 4 * i) * NP);
; #pragma unroll
;         for (int ks = 0; ks < 8; ++ks) kn[ks] = *(const bf16x8*)(kbase + (size_t)sn * NP + 16 * ks);
;         f32x16 z;
; #pragma unroll
;         for (int r = 0; r < 16; ++r) z[r] = 0.f;
; #pragma unroll
;         for (int ks = 0; ks < 8; ++ks) z = MFMA32(kf[ks], qf[ks], z);
;     ...
;             for (int r = 0; r < 16; ++r) { const float ex = __builtin_amdgcn_exp2f(fminf(z[r] * 1.44269504f, 80.f)); const float w = __builtin_amdgcn_rcpf(1.0f + ex);
;                 const bool valid = (s0 + crow(r, hh)) < t; om[r] = valid ? w : 1.f; be[r] = valid ? ex * w : 0.f; }
.LBB0_536:
	s_or_b32 s33, s35, s30
	s_lshl_b32 s56, s33, 5
	s_and_b64 vcc, exec, s[6:7]
	v_or_b32_e32 v203, s56, v1
	s_cbranch_vccnz .LBB0_534
	v_mad_i64_i32 v[18:19], s[8:9], s56, v199, v[186:187]
	v_mov_b64_e32 v[2:3], s[24:25]
	global_load_dwordx4 v[82:85], v[18:19], off
	v_mad_i64_i32 v[2:3], s[8:9], v203, s27, v[2:3]
	v_lshl_add_u64 v[2:3], v[2:3], 0, s[50:51]
	v_lshl_add_u64 v[2:3], v[2:3], 0, v[180:181]
	v_add_co_u32_e32 v4, vcc, s28, v2
	v_lshl_add_u64 v[20:21], v[2:3], 0, s[70:71]
	s_nop 0
	v_addc_co_u32_e32 v5, vcc, 0, v3, vcc
	global_load_dwordx4 v[86:89], v[4:5], off
	global_load_dwordx4 v[110:113], v[18:19], off offset:32
	global_load_dwordx4 v[90:93], v[20:21], off offset:32
	global_load_dwordx4 v[114:117], v[18:19], off offset:64
	global_load_dwordx4 v[94:97], v[20:21], off offset:64
	global_load_dwordx4 v[118:121], v[18:19], off offset:96
	global_load_dwordx4 v[98:101], v[20:21], off offset:96
	global_load_dwordx4 v[122:125], v[18:19], off offset:128
	global_load_dwordx4 v[102:105], v[20:21], off offset:128
	global_load_dwordx4 v[126:129], v[18:19], off offset:160
	global_load_dwordx4 v[106:109], v[20:21], off offset:160
	global_load_dwordx4 v[130:133], v[18:19], off offset:192
	global_load_dwordx4 v[134:137], v[20:21], off offset:192
	global_load_dwordx4 v[142:145], v[18:19], off offset:224
	global_load_dwordx4 v[138:141], v[20:21], off offset:224
	v_mad_u64_u32 v[18:19], s[8:9], s56, v199, v[188:189]
	v_cmp_lt_i32_e32 vcc, v201, v202
	s_or_b32 s8, s56, 4
	s_or_b32 s10, s56, 8
	s_or_b32 s11, s56, 12
	s_or_b32 s12, s56, 16
	s_or_b32 s13, s56, 20
	s_or_b32 s14, s56, 24
	s_or_b32 s15, s56, 28
	v_cndmask_b32_e32 v20, v200, v201, vcc
	v_mad_u64_u32 v[22:23], s[8:9], s8, v199, v[188:189]
	v_mad_u64_u32 v[26:27], s[8:9], s10, v199, v[188:189]
	v_mad_u64_u32 v[30:31], s[8:9], s11, v199, v[188:189]
	v_mad_u64_u32 v[34:35], s[8:9], s12, v199, v[188:189]
	v_mad_u64_u32 v[38:39], s[8:9], s13, v199, v[188:189]
	v_mad_u64_u32 v[42:43], s[8:9], s14, v199, v[188:189]
	v_mad_u64_u32 v[46:47], s[8:9], s15, v199, v[188:189]
	v_lshlrev_b32_e32 v204, 2, v20
	global_load_dwordx4 v[18:21], v[18:19], off
	s_nop 0
	global_load_dwordx4 v[22:25], v[22:23], off
	s_nop 0
	global_load_dwordx4 v[26:29], v[26:27], off
	s_nop 0
	global_load_dwordx4 v[30:33], v[30:31], off
	s_nop 0
	global_load_dwordx4 v[34:37], v[34:35], off
	s_nop 0
	global_load_dwordx4 v[38:41], v[38:39], off
	s_nop 0
	global_load_dwordx4 v[42:45], v[42:43], off
	s_nop 0
	global_load_dwordx4 v[46:49], v[46:47], off
	v_or_b32_e32 v52, s56, v179
	v_or_b32_e32 v55, 11, v52
	v_or_b32_e32 v56, 18, v52
	v_cmp_lt_i32_e64 s[8:9], v55, v203
	v_cmp_lt_i32_e64 s[12:13], v56, v203
	v_or_b32_e32 v51, 2, v52
	v_or_b32_e32 v50, 3, v52
	v_cmp_lt_i32_e32 vcc, v50, v203
	v_cmp_lt_i32_e64 s[10:11], v51, v203
	v_or_b32_e32 v57, 19, v52
	v_or_b32_e32 v53, 10, v52
	v_or_b32_e32 v54, 1, v52
	s_cmp_eq_u32 s33, 0
	s_waitcnt vmcnt(22)
	v_mfma_f32_32x32x16_bf16 v[2:17], v[82:85], v[86:89], 0
	s_waitcnt vmcnt(7)
	ds_write_b128 v197, v[18:21]
	s_waitcnt vmcnt(6)
	ds_write_b128 v197, v[22:25] offset:1088
	s_waitcnt vmcnt(5)
	ds_write_b128 v197, v[26:29] offset:2176
	s_waitcnt vmcnt(4)
	ds_write_b128 v197, v[30:33] offset:3264
	s_waitcnt vmcnt(3)
	ds_write_b128 v197, v[34:37] offset:4352
	s_waitcnt vmcnt(2)
	ds_write_b128 v197, v[38:41] offset:5440
	s_waitcnt vmcnt(1)
	ds_write_b128 v197, v[42:45] offset:6528
	s_waitcnt vmcnt(0)
	ds_write_b128 v197, v[46:49] offset:7616
	v_mfma_f32_32x32x16_bf16 v[2:17], v[110:113], v[90:93], v[2:17]
	v_mfma_f32_32x32x16_bf16 v[2:17], v[114:117], v[94:97], v[2:17]
	v_mfma_f32_32x32x16_bf16 v[2:17], v[118:121], v[98:101], v[2:17]
	v_mfma_f32_32x32x16_bf16 v[2:17], v[122:125], v[102:105], v[2:17]
	v_mfma_f32_32x32x16_bf16 v[2:17], v[126:129], v[106:109], v[2:17]
	v_mfma_f32_32x32x16_bf16 v[2:17], v[130:133], v[134:137], v[2:17]
	v_mfma_f32_32x32x16_bf16 v[2:17], v[142:145], v[138:141], v[2:17]
	s_sub_i32 s100, s56, 32
	s_cmp_eq_u32 s33, 0
	s_cselect_b32 s100, 0, s100
	s_nop 0
	v_mad_i64_i32 v[238:239], s[98:99], s100, v199, v[186:187]
	s_nop 0
	global_load_dwordx4 v[82:85], v[238:239], off
	global_load_dwordx4 v[110:113], v[238:239], off offset:32
	global_load_dwordx4 v[114:117], v[238:239], off offset:64
	global_load_dwordx4 v[118:121], v[238:239], off offset:96
	global_load_dwordx4 v[122:125], v[238:239], off offset:128
	global_load_dwordx4 v[126:129], v[238:239], off offset:160
	global_load_dwordx4 v[130:133], v[238:239], off offset:192
	global_load_dwordx4 v[142:145], v[238:239], off offset:224
	s_cmp_eq_u32 s33, 0
	s_nop 11
	v_mul_f32_e32 v5, 0x3fb8aa3b, v5
	v_mul_f32_e32 v7, 0x3fb8aa3b, v7
	v_mul_f32_e32 v11, 0x3fb8aa3b, v11
	v_mul_f32_e32 v12, 0x3fb8aa3b, v12
	v_min_f32_e32 v5, 0x42a00000, v5
	v_min_f32_e32 v7, 0x42a00000, v7
	v_min_f32_e32 v11, 0x42a00000, v11
	v_min_f32_e32 v12, 0x42a00000, v12
	v_exp_f32_e32 v59, v5
	v_exp_f32_e32 v5, v7
	v_exp_f32_e32 v7, v11
	v_exp_f32_e32 v61, v12
	v_mul_f32_e32 v8, 0x3fb8aa3b, v8
	v_mul_f32_e32 v9, 0x3fb8aa3b, v9
	v_mul_f32_e32 v13, 0x3fb8aa3b, v13
	v_mul_f32_e32 v15, 0x3fb8aa3b, v15
	v_min_f32_e32 v8, 0x42a00000, v8
	v_min_f32_e32 v9, 0x42a00000, v9
	v_min_f32_e32 v13, 0x42a00000, v13
	v_min_f32_e32 v15, 0x42a00000, v15
	v_exp_f32_e32 v67, v8
	v_exp_f32_e32 v60, v9
	v_mul_f32_e32 v16, 0x3fb8aa3b, v16
	v_exp_f32_e32 v64, v13
	v_exp_f32_e32 v9, v15
	v_add_f32_e32 v13, 1.0, v59
	v_add_f32_e32 v15, 1.0, v5
	v_add_f32_e32 v66, 1.0, v7
	v_add_f32_e32 v68, 1.0, v61
	v_min_f32_e32 v16, 0x42a00000, v16
	v_rcp_f32_e32 v72, v13
	v_rcp_f32_e32 v13, v15
	v_rcp_f32_e32 v15, v66
	v_rcp_f32_e32 v66, v68
	v_mul_f32_e32 v14, 0x3fb8aa3b, v14
; __device__ __forceinline__ int crow(int r, int hi) { return (r & 3) + 8 * (r >> 2) + 4 * hi; }
; __device__ __forceinline__ void sb_unit(LAS unsigned char* vs, const bf16* P, bf16* YB, int hd, int qb, int lane) {
;     ...
;             for (int r = 0; r < 16; ++r) { const float ex = __builtin_amdgcn_exp2f(fminf(z[r] * 1.44269504f, 80.f)); const float w = __builtin_amdgcn_rcpf(1.0f + ex);
;                 const bool valid = (s0 + crow(r, hh)) < t; om[r] = valid ? w : 1.f; be[r] = valid ? ex * w : 0.f; }
;         } else {
; #pragma unroll
;             for (int r = 0; r < 16; ++r) { const float ex = __builtin_amdgcn_exp2f(fminf(z[r] * 1.44269504f, 80.f)); const float w = __builtin_amdgcn_rcpf(1.0f + ex); om[r] = w; be[r] = ex * w; }
;         }
;         float e[16], tot[4], otot[4];
; #pragma unroll
;         for (int g = 0; g < 4; ++g) { e[4 * g + 3] = 1.f; e[4 * g + 2] = om[4 * g + 3]; e[4 * g + 1] = e[4 * g + 2] * om[4 * g + 2]; e[4 * g] = e[4 * g + 1] * om[4 * g + 1]; tot[g] = e[4 * g] * om[4 * g]; }
; #pragma unroll
;         for (int g = 0; g < 4; ++g) otot[g] = __shfl_xor(tot[g], 32);
	v_exp_f32_e32 v62, v16
	v_mul_f32_e32 v17, 0x3fb8aa3b, v17
	v_mul_f32_e32 v4, 0x3fb8aa3b, v4
	v_min_f32_e32 v14, 0x42a00000, v14
	v_add_f32_e32 v16, 1.0, v67
	v_add_f32_e32 v63, 1.0, v60
	v_min_f32_e32 v17, 0x42a00000, v17
	v_mul_f32_e32 v6, 0x3fb8aa3b, v6
	v_mul_f32_e32 v10, 0x3fb8aa3b, v10
	v_min_f32_e32 v4, 0x42a00000, v4
	v_exp_f32_e32 v8, v14
	v_rcp_f32_e32 v73, v16
	v_rcp_f32_e32 v16, v63
	v_exp_f32_e32 v76, v17
	v_min_f32_e32 v6, 0x42a00000, v6
	v_min_f32_e32 v10, 0x42a00000, v10
	v_exp_f32_e32 v58, v4
	v_mul_f32_e32 v55, v61, v66
	v_exp_f32_e32 v4, v6
	v_exp_f32_e32 v6, v10
	v_cndmask_b32_e64 v75, 0, v55, s[12:13]
	v_add_f32_e32 v55, 1.0, v62
	v_rcp_f32_e32 v55, v55
	v_add_f32_e32 v70, 1.0, v8
	v_cndmask_b32_e64 v50, 1.0, v16, s[8:9]
	v_mul_f32_e32 v16, v60, v16
	v_add_f32_e32 v51, 1.0, v9
	v_add_f32_e32 v60, 1.0, v76
	v_add_f32_e32 v12, 1.0, v58
	v_cndmask_b32_e32 v74, 1.0, v72, vcc
	v_mul_f32_e32 v59, v59, v72
	v_cndmask_b32_e64 v72, 0, v16, s[8:9]
	v_rcp_f32_e32 v16, v70
	v_rcp_f32_e32 v17, v51
	v_rcp_f32_e32 v77, v60
	v_add_f32_e32 v14, 1.0, v4
	v_add_f32_e32 v65, 1.0, v6
	v_rcp_f32_e32 v71, v12
	v_or_b32_e32 v51, 26, v52
	v_rcp_f32_e32 v12, v14
	v_rcp_f32_e32 v14, v65
	v_mul_f32_e32 v56, v62, v55
	v_cmp_lt_i32_e64 s[8:9], v51, v203
	v_or_b32_e32 v51, 27, v52
	v_add_f32_e32 v69, 1.0, v64
	v_cndmask_b32_e32 v59, 0, v59, vcc
	v_cndmask_b32_e64 v78, 0, v56, s[8:9]
	v_cmp_lt_i32_e32 vcc, v51, v203
	v_cndmask_b32_e64 v51, 1.0, v55, s[8:9]
	v_or_b32_e32 v55, 25, v52
	v_or_b32_e32 v56, 24, v52
	v_rcp_f32_e32 v68, v69
	v_cndmask_b32_e32 v79, 1.0, v77, vcc
	v_pk_mul_f32 v[8:9], v[8:9], v[16:17]
	v_cmp_lt_i32_e64 s[8:9], v55, v203
	v_cmp_lt_i32_e64 s[14:15], v56, v203
	v_mul_f32_e32 v58, v58, v71
	v_cndmask_b32_e64 v61, 0, v9, s[8:9]
	v_cndmask_b32_e64 v60, 0, v8, s[14:15]
	v_cndmask_b32_e64 v8, 1.0, v17, s[8:9]
	v_cndmask_b32_e64 v9, 1.0, v16, s[14:15]
	v_mul_f32_e32 v63, v79, v51
	v_or_b32_e32 v16, 17, v52
	v_mul_f32_e32 v3, 0x3fb8aa3b, v3
	v_cndmask_b32_e64 v58, 0, v58, s[10:11]
	v_mul_f32_e32 v62, v8, v63
	v_cndmask_b32_e64 v55, 1.0, v71, s[10:11]
	v_or_b32_e32 v17, 16, v52
	v_pk_mul_f32 v[6:7], v[6:7], v[14:15]
	v_cmp_lt_i32_e64 s[10:11], v16, v203
	v_mul_f32_e32 v2, 0x3fb8aa3b, v2
	v_min_f32_e32 v3, 0x42a00000, v3
	v_mul_f32_e32 v65, v9, v62
	v_cmp_lt_i32_e64 s[8:9], v57, v203
	v_cndmask_b32_e64 v9, 1.0, v66, s[12:13]
	v_cndmask_b32_e64 v69, 0, v7, s[10:11]
	v_cmp_lt_i32_e64 s[12:13], v17, v203
	v_or_b32_e32 v7, 8, v52
	v_min_f32_e32 v2, 0x42a00000, v2
	v_exp_f32_e32 v3, v3
	v_cndmask_b32_e64 v80, 1.0, v68, s[8:9]
	v_mul_f32_e32 v81, v64, v68
	v_cndmask_b32_e64 v68, 0, v6, s[12:13]
	v_or_b32_e32 v6, 9, v52
	v_pk_mul_f32 v[4:5], v[4:5], v[12:13]
	v_cmp_lt_i32_e64 s[16:17], v7, v203
	v_exp_f32_e32 v2, v2
	v_cmp_lt_i32_e64 s[14:15], v6, v203
	v_cndmask_b32_e64 v4, 0, v4, s[16:17]
	v_cndmask_b32_e64 v64, 1.0, v12, s[16:17]
	v_mul_f32_e32 v6, v67, v73
	v_cmp_lt_i32_e64 s[16:17], v53, v203
	v_mul_f32_e32 v51, v80, v9
	v_cndmask_b32_e64 v7, 1.0, v15, s[10:11]
	v_cndmask_b32_e64 v56, 0, v6, s[16:17]
	v_cndmask_b32_e64 v6, 1.0, v73, s[16:17]
	v_cndmask_b32_e64 v15, 1.0, v14, s[12:13]
	v_cndmask_b32_e64 v14, 1.0, v13, s[14:15]
	v_pk_mul_f32 v[70:71], v[6:7], v[50:51]
	v_add_f32_e32 v11, 1.0, v3
	v_pk_mul_f32 v[6:7], v[14:15], v[70:71]
	v_add_f32_e32 v10, 1.0, v2
	v_rcp_f32_e32 v11, v11
	ds_bpermute_b32 v8, v204, v65
	ds_bpermute_b32 v12, v204, v7
	v_pk_mul_f32 v[14:15], v[64:65], v[6:7]
	v_rcp_f32_e32 v10, v10
	ds_bpermute_b32 v16, v204, v14
	v_cmp_lt_i32_e64 s[10:11], v54, v203
	v_mul_f32_e32 v9, v74, v55
	v_pk_mul_f32 v[2:3], v[2:3], v[10:11]
	v_cndmask_b32_e64 v13, 1.0, v11, s[10:11]
	v_cndmask_b32_e64 v17, 1.0, v10, s[4:5]
	s_waitcnt lgkmcnt(1)
; #define LAS __attribute__((address_space(3)))
; __device__ __forceinline__ s16x4 ds_tr(LAS const unsigned char* p) { return __builtin_bit_cast(s16x4, __builtin_amdgcn_ds_read_tr16_b64_v4i16((LAS v4i16_t*)p)); }
; __device__ __forceinline__ bf16x8 cat8(s16x4 lo, s16x4 hi) { return (bf16x8){lo[0], lo[1], lo[2], lo[3], hi[0], hi[1], hi[2], hi[3]}; }
; #define MFMA32(a, b, c) __builtin_amdgcn_mfma_f32_32x32x16_bf16((a), (b), (c), 0, 0, 0)
; __device__ __forceinline__ void sb_unit(LAS unsigned char* vs, const bf16* P, bf16* YB, int hd, int qb, int lane) {
;     ...
;         for (int g = 0; g < 4; ++g) { e[4 * g + 3] = 1.f; e[4 * g + 2] = om[4 * g + 3]; e[4 * g + 1] = e[4 * g + 2] * om[4 * g + 2]; e[4 * g] = e[4 * g + 1] * om[4 * g + 1]; tot[g] = e[4 * g] * om[4 * g]; }
; #pragma unroll
;         for (int g = 0; g < 4; ++g) otot[g] = __shfl_xor(tot[g], 32);
;         float so[4], xe[4], base[4];
;         so[3] = 1.f; so[2] = tot[3]; so[1] = so[2] * tot[2]; so[0] = so[1] * tot[1];
;         xe[3] = 1.f; xe[2] = otot[3]; xe[1] = xe[2] * otot[2]; xe[0] = xe[1] * otot[1];
; #pragma unroll
;         for (int g = 0; g < 4; ++g) base[g] = R * so[g] * (hh == 0 ? xe[g] * otot[g] : xe[g]);
;         const float total = (so[0] * tot[0]) * (xe[0] * otot[0]);
;         float p[16];
; #pragma unroll
;         for (int r = 0; r < 16; ++r) p[r] = be[r] * ((r & 3) == 3 ? base[r >> 2] : base[r >> 2] * e[r]);
;         const bf16x8 pf0 = pack8(p[0], p[1], p[2], p[3], p[4], p[5], p[6], p[7]), pf1 = pack8(p[8], p[9], p[10], p[11], p[12], p[13], p[14], p[15]);
; #pragma unroll
;         for (int i = 0; i < 8; ++i) *(LAS u32x4*)(vs + (4 * i + (lane >> 4)) * KS_STRIDE + (lane & 15) * 16) = vr[i];
;         bf16x8 vf[4][2];
; #pragma unroll
;         for (int cb = 0; cb < 4; ++cb)
; #pragma unroll
;             for (int sp = 0; sp < 2; ++sp) { const int rlo = 16 * sp + 4 * hh + q4, rhi = rlo + 8; const int vcol = (32 * cb + 16 * g2 + 4 * p4) * 2;
;                 vf[cb][sp] = cat8(ds_tr(vs + rlo * KS_STRIDE + vcol), ds_tr(vs + rhi * KS_STRIDE + vcol)); }
; #pragma unroll
;         for (int sp = 0; sp < 2; ++sp)
; #pragma unroll
;             for (int cb = 0; cb < 4; ++cb) o[cb] = MFMA32(vf[cb][sp], sp ? pf1 : pf0, o[cb]);
;         R *= total;
;         if (__all(R == 0.f)) break;
	v_pk_mul_f32 v[10:11], v[12:13], v[8:9]
	v_pk_mul_f32 v[52:53], v[14:15], v[14:15] op_sel:[0,1] op_sel_hi:[1,0]
	s_waitcnt lgkmcnt(0)
	v_pk_mul_f32 v[12:13], v[10:11], v[16:17]
	ds_bpermute_b32 v14, v204, v13
	v_cndmask_b32_e64 v66, 1.0, v8, s[0:1]
	v_cndmask_b32_e64 v64, v8, v10, s[0:1]
	v_cndmask_b32_e64 v8, v10, v12, s[0:1]
	v_mul_f32_e32 v10, v8, v15
	v_mov_b32_e32 v15, v52
	s_waitcnt lgkmcnt(0)
	v_pk_mul_f32 v[150:151], v[12:13], v[14:15]
	v_mov_b32_e32 v7, v70
	v_cndmask_b32_e64 v8, v12, v150, s[0:1]
	v_mul_f32_e32 v12, v8, v52
	v_mov_b32_e32 v8, v11
	v_cndmask_b32_e64 v5, 0, v5, s[14:15]
	v_cndmask_b32_e64 v3, 0, v3, s[10:11]
	v_cndmask_b32_e64 v2, 0, v2, s[4:5]
	v_pk_mul_f32 v[8:9], v[8:9], v[12:13] op_sel_hi:[1,0]
	v_pk_mul_f32 v[6:7], v[6:7], v[10:11] op_sel_hi:[1,0]
	v_pk_mul_f32 v[2:3], v[2:3], v[8:9]
	v_mul_f32_e32 v8, v74, v12
	v_pk_mul_f32 v[6:7], v[4:5], v[6:7]
	v_mul_f32_e32 v4, v50, v10
	v_mul_f32_e32 v8, v58, v8
	v_mul_f32_e32 v9, v59, v12
	v_mul_f32_e32 v11, v56, v4
	v_cvt_pk_bf16_f32 v52, v2, v3
	ds_read_b64_tr_b16 v[2:3], v198
	ds_read_b64_tr_b16 v[4:5], v198 offset:2176
	ds_read_b64_tr_b16 v[18:19], v198 offset:64
	ds_read_b64_tr_b16 v[34:35], v198 offset:128
	ds_read_b64_tr_b16 v[56:57], v198 offset:192
	ds_read_b64_tr_b16 v[20:21], v198 offset:2240
	ds_read_b64_tr_b16 v[36:37], v198 offset:2304
	ds_read_b64_tr_b16 v[58:59], v198 offset:2368
	v_cndmask_b32_e64 v67, 0, v81, s[8:9]
	v_mul_f32_e32 v22, v76, v77
	v_cndmask_b32_e32 v38, 0, v22, vcc
	v_mov_b32_e32 v50, v71
	v_pk_mul_f32 v[22:23], v[66:67], v[62:63] op_sel_hi:[0,1]
	v_mul_f32_e32 v39, v66, v79
	v_mul_f32_e32 v62, v64, v65
	v_mul_f32_e32 v10, v72, v10
	v_mul_f32_e32 v74, v78, v39
	v_mul_f32_e32 v76, v66, v38
	v_pk_mul_f32 v[38:39], v[50:51], v[62:63] op_sel_hi:[1,0]
	v_mul_f32_e32 v63, v80, v62
	v_cvt_pk_bf16_f32 v53, v8, v9
	v_cvt_pk_bf16_f32 v54, v6, v7
	v_cvt_pk_bf16_f32 v55, v11, v10
	v_pk_mul_f32 v[60:61], v[60:61], v[22:23]
	v_pk_mul_f32 v[50:51], v[68:69], v[38:39]
	v_mul_f32_e32 v63, v75, v63
	v_mul_f32_e32 v62, v67, v62
	s_waitcnt lgkmcnt(6)
	v_mfma_f32_32x32x16_bf16 v[2:17], v[2:5], v[52:55], 0
	v_cvt_pk_bf16_f32 v66, v50, v51
	v_cvt_pk_bf16_f32 v67, v63, v62
	v_cvt_pk_bf16_f32 v68, v60, v61
	ds_read_b64_tr_b16 v[70:71], v198 offset:4352
	ds_read_b64_tr_b16 v[72:73], v198 offset:6528
	v_cvt_pk_bf16_f32 v69, v74, v76
	ds_read_b64_tr_b16 v[74:75], v198 offset:4416
	ds_read_b64_tr_b16 v[78:79], v198 offset:4480
	ds_read_b64_tr_b16 v[146:147], v198 offset:4544
	ds_read_b64_tr_b16 v[76:77], v198 offset:6592
	ds_read_b64_tr_b16 v[80:81], v198 offset:6656
	ds_read_b64_tr_b16 v[148:149], v198 offset:6720
	v_mul_f32_e32 v190, v150, v151
	s_waitcnt lgkmcnt(10)
	v_mfma_f32_32x32x16_bf16 v[18:33], v[18:21], v[52:55], 0
	v_cmp_eq_f32_e32 vcc, 0, v190
	s_cselect_b64 s[8:9], -1, 0
	s_cmp_eq_u64 vcc, exec
	s_cselect_b64 vcc, -1, 0
	s_waitcnt lgkmcnt(9)
	v_mfma_f32_32x32x16_bf16 v[34:49], v[34:37], v[52:55], 0
	s_waitcnt lgkmcnt(8)
	v_mfma_f32_32x32x16_bf16 v[50:65], v[56:59], v[52:55], 0
	s_waitcnt lgkmcnt(6)
	v_mfma_f32_32x32x16_bf16 v[2:17], v[70:73], v[66:69], v[2:17]
	s_waitcnt lgkmcnt(2)
	v_mfma_f32_32x32x16_bf16 v[18:33], v[74:77], v[66:69], v[18:33]
	s_waitcnt lgkmcnt(1)
	v_mfma_f32_32x32x16_bf16 v[34:49], v[78:81], v[66:69], v[34:49]
	s_waitcnt lgkmcnt(0)
	v_mfma_f32_32x32x16_bf16 v[50:65], v[146:149], v[66:69], v[50:65]
	s_cbranch_vccnz .LBB0_539

; __device__ __forceinline__ int crow(int r, int hi) { return (r & 3) + 8 * (r >> 2) + 4 * hi; }
; #define MFMA32(a, b, c) __builtin_amdgcn_mfma_f32_32x32x16_bf16((a), (b), (c), 0, 0, 0)
; __device__ __forceinline__ void sb_unit(LAS unsigned char* vs, const bf16* P, bf16* YB, int hd, int qb, int lane) {
;     ...
;         const int s0 = 32 * kt, sn = kt > 0 ? s0 - 32 : s0;
;         bf16x8 kn[8]; u32x4 vr[8];
; #pragma unroll
;         for (int i = 0; i < 8; ++i) vr[i] = *(const u32x4*)(vbase + (size_t)(s0 + 4 * i) * NP);
; #pragma unroll
;         for (int ks = 0; ks < 8; ++ks) kn[ks] = *(const bf16x8*)(kbase + (size_t)sn * NP + 16 * ks);
;         f32x16 z;
; #pragma unroll
;         for (int r = 0; r < 16; ++r) z[r] = 0.f;
; #pragma unroll
;         for (int ks = 0; ks < 8; ++ks) z = MFMA32(kf[ks], qf[ks], z);
;         float om[16], be[16];
;         if (kt == qb) {
; #pragma unroll
;             for (int r = 0; r < 16; ++r) { const float ex = __builtin_amdgcn_exp2f(fminf(z[r] * 1.44269504f, 80.f)); const float w = __builtin_amdgcn_rcpf(1.0f + ex);
;                 const bool valid = (s0 + crow(r, hh)) < t; om[r] = valid ? w : 1.f; be[r] = valid ? ex * w : 0.f; }
;         } else {
; #pragma unroll
;             for (int r = 0; r < 16; ++r) { const float ex = __builtin_amdgcn_exp2f(fminf(z[r] * 1.44269504f, 80.f)); const float w = __builtin_amdgcn_rcpf(1.0f + ex); om[r] = w; be[r] = ex * w; }
;         }
.LBB0_542:
	s_waitcnt vmcnt(7)
	v_mfma_f32_32x32x16_bf16 v[66:81], v[82:85], v[86:89], 0
	s_add_i32 s8, s10, -4
	s_nop 0
	v_mad_u64_u32 v[146:147], s[8:9], s8, v199, v[188:189]
	s_nop 0
	v_mad_u64_u32 v[150:151], s[8:9], s10, v199, v[188:189]
	s_nop 0
	s_add_i32 s8, s10, 4
	s_nop 0
	v_mad_u64_u32 v[154:155], s[8:9], s8, v199, v[188:189]
	s_nop 0
	s_add_i32 s8, s10, 8
	s_nop 0
	v_mad_u64_u32 v[158:159], s[8:9], s8, v199, v[188:189]
	s_nop 0
	s_add_i32 s8, s10, 12
	s_nop 0
	v_mad_u64_u32 v[162:163], s[8:9], s8, v199, v[188:189]
	s_nop 0
	s_add_i32 s8, s10, 16
	s_nop 0
	v_mad_u64_u32 v[166:167], s[8:9], s8, v199, v[188:189]
	s_nop 0
	s_add_i32 s8, s10, 20
	s_nop 0
	v_mad_u64_u32 v[170:171], s[8:9], s8, v199, v[188:189]
	s_nop 0
	s_add_i32 s8, s10, 24
	s_nop 0
	v_mad_u64_u32 v[174:175], s[8:9], s8, v199, v[188:189]
	s_nop 0
	global_load_dwordx4 v[146:149], v[146:147], off
	s_nop 0
	global_load_dwordx4 v[150:153], v[150:151], off
	s_nop 0
	global_load_dwordx4 v[154:157], v[154:155], off
	s_nop 0
	global_load_dwordx4 v[158:161], v[158:159], off
	s_nop 0
	global_load_dwordx4 v[162:165], v[162:163], off
	s_nop 0
	global_load_dwordx4 v[166:169], v[166:167], off
	s_nop 0
	global_load_dwordx4 v[170:173], v[170:171], off
	s_nop 0
	global_load_dwordx4 v[174:177], v[174:175], off
	s_nop 0
	s_waitcnt vmcnt(14)
	v_mfma_f32_32x32x16_bf16 v[66:81], v[110:113], v[90:93], v[66:81]
	s_waitcnt vmcnt(13)
	v_mfma_f32_32x32x16_bf16 v[66:81], v[114:117], v[94:97], v[66:81]
	s_waitcnt vmcnt(12)
	v_mfma_f32_32x32x16_bf16 v[66:81], v[118:121], v[98:101], v[66:81]
	s_waitcnt vmcnt(11)
	v_mfma_f32_32x32x16_bf16 v[66:81], v[122:125], v[102:105], v[66:81]
	s_waitcnt vmcnt(10)
	v_mfma_f32_32x32x16_bf16 v[66:81], v[126:129], v[106:109], v[66:81]
	s_waitcnt vmcnt(9)
	v_mfma_f32_32x32x16_bf16 v[66:81], v[130:133], v[134:137], v[66:81]
	s_waitcnt vmcnt(8)
	v_mfma_f32_32x32x16_bf16 v[66:81], v[142:145], v[138:141], v[66:81]
	s_sub_i32 s100, s10, 36
	s_cmp_lg_u32 s33, 1
	s_cselect_b32 s100, s100, 0
	s_nop 0
	v_mad_i64_i32 v[238:239], s[98:99], s100, v199, v[186:187]
	s_nop 0
	global_load_dwordx4 v[82:85], v[238:239], off
	global_load_dwordx4 v[110:113], v[238:239], off offset:32
	global_load_dwordx4 v[114:117], v[238:239], off offset:64
	global_load_dwordx4 v[118:121], v[238:239], off offset:96
	global_load_dwordx4 v[122:125], v[238:239], off offset:128
	global_load_dwordx4 v[126:129], v[238:239], off offset:160
	global_load_dwordx4 v[130:133], v[238:239], off offset:192
	global_load_dwordx4 v[142:145], v[238:239], off offset:224
	s_waitcnt vmcnt(15)
	ds_write_b128 v197, v[146:149]
	s_waitcnt vmcnt(14)
	ds_write_b128 v197, v[150:153] offset:1088
	s_waitcnt vmcnt(13)
	ds_write_b128 v197, v[154:157] offset:2176
	s_waitcnt vmcnt(12)
	ds_write_b128 v197, v[158:161] offset:3264
	s_waitcnt vmcnt(11)
	ds_write_b128 v197, v[162:165] offset:4352
	s_waitcnt vmcnt(10)
	ds_write_b128 v197, v[166:169] offset:5440
	s_waitcnt vmcnt(9)
	ds_write_b128 v197, v[170:173] offset:6528
	s_waitcnt vmcnt(8)
	ds_write_b128 v197, v[174:177] offset:7616
	s_nop 11
	v_mul_f32_e32 v68, 0x3fb8aa3b, v68
	v_mul_f32_e32 v69, 0x3fb8aa3b, v69
	v_min_f32_e32 v68, 0x42a00000, v68
	v_min_f32_e32 v69, 0x42a00000, v69
	v_mul_f32_e32 v66, 0x3fb8aa3b, v66
	v_mul_f32_e32 v71, 0x3fb8aa3b, v71
	v_exp_f32_e32 v208, v68
	v_exp_f32_e32 v209, v69
	v_min_f32_e32 v66, 0x42a00000, v66
	v_min_f32_e32 v71, 0x42a00000, v71
	v_exp_f32_e32 v206, v66
	v_exp_f32_e32 v211, v71
	v_add_f32_e32 v68, 1.0, v208
	v_add_f32_e32 v69, 1.0, v209
	v_rcp_f32_e32 v216, v68
	v_rcp_f32_e32 v217, v69
	v_mul_f32_e32 v68, 0x3fb8aa3b, v73
	v_mul_f32_e32 v69, 0x3fb8aa3b, v75
	v_mul_f32_e32 v73, 0x3fb8aa3b, v78
	v_mul_f32_e32 v75, 0x3fb8aa3b, v79
	v_add_f32_e32 v66, 1.0, v206
	v_add_f32_e32 v71, 1.0, v211
	v_min_f32_e32 v73, 0x42a00000, v73
	v_min_f32_e32 v75, 0x42a00000, v75
	v_mul_f32_e32 v67, 0x3fb8aa3b, v67
	v_rcp_f32_e32 v214, v66
	v_rcp_f32_e32 v66, v71
	v_mul_f32_e32 v71, 0x3fb8aa3b, v76
	v_exp_f32_e32 v76, v73
	v_mul_f32_e32 v73, 0x3fb8aa3b, v77
	v_exp_f32_e32 v77, v75
	v_mul_f32_e32 v75, 0x3fb8aa3b, v80
	v_mul_f32_e32 v72, 0x3fb8aa3b, v72
	v_min_f32_e32 v67, 0x42a00000, v67
	v_min_f32_e32 v75, 0x42a00000, v75
	v_mul_f32_e32 v78, 0x3fb8aa3b, v81
	v_mul_f32_e32 v70, 0x3fb8aa3b, v70
	v_min_f32_e32 v72, 0x42a00000, v72
	v_exp_f32_e32 v207, v67
	v_exp_f32_e32 v75, v75
	v_min_f32_e32 v78, 0x42a00000, v78
	v_min_f32_e32 v70, 0x42a00000, v70
	v_exp_f32_e32 v212, v72
	v_min_f32_e32 v68, 0x42a00000, v68
	v_min_f32_e32 v71, 0x42a00000, v71
	v_min_f32_e32 v73, 0x42a00000, v73
	v_exp_f32_e32 v191, v78
	v_exp_f32_e32 v210, v70
	v_exp_f32_e32 v213, v68
	v_exp_f32_e32 v220, v71
	v_exp_f32_e32 v221, v73
	v_mul_f32_e32 v68, 0x3fb8aa3b, v74
	v_min_f32_e32 v69, 0x42a00000, v69
	v_add_f32_e32 v67, 1.0, v207
	v_min_f32_e32 v68, 0x42a00000, v68
	v_exp_f32_e32 v69, v69
	v_add_f32_e32 v79, 1.0, v75
	v_rcp_f32_e32 v215, v67
	v_add_f32_e32 v67, 1.0, v212
	v_exp_f32_e32 v68, v68
	v_add_f32_e32 v73, 1.0, v76
	v_add_f32_e32 v78, 1.0, v77
	v_rcp_f32_e32 v81, v79
	v_add_f32_e32 v79, 1.0, v191
	v_add_f32_e32 v70, 1.0, v210
	v_rcp_f32_e32 v74, v67
	v_add_f32_e32 v67, 1.0, v213
	v_add_f32_e32 v72, 1.0, v220
	v_rcp_f32_e32 v223, v79
	v_rcp_f32_e32 v79, v78
	v_rcp_f32_e32 v78, v73
	v_add_f32_e32 v73, 1.0, v221
	v_rcp_f32_e32 v218, v70
	v_rcp_f32_e32 v70, v67
	v_rcp_f32_e32 v72, v72
	v_rcp_f32_e32 v73, v73
	v_add_f32_e32 v71, 1.0, v69
	v_add_f32_e32 v67, 1.0, v68
	v_rcp_f32_e32 v71, v71
	v_rcp_f32_e32 v67, v67
	v_mul_f32_e32 v225, v223, v81
	v_mul_f32_e32 v226, v75, v81
	v_mul_f32_e32 v233, v73, v72
	v_mov_b32_e32 v75, v70
	v_mul_f32_e32 v224, v79, v225
	v_pk_mul_f32 v[228:229], v[76:77], v[78:79]
	v_pk_mul_f32 v[76:77], v[212:213], v[74:75]
	v_mov_b32_e32 v75, v233
	v_mul_f32_e32 v178, v78, v224
	v_pk_mul_f32 v[212:213], v[70:71], v[74:75]
	v_mov_b32_e32 v219, v66
	v_pk_mul_f32 v[74:75], v[66:67], v[212:213]
	v_pk_mul_f32 v[210:211], v[210:211], v[218:219]
	v_mov_b32_e32 v219, v178
	ds_bpermute_b32 v80, v204, v178
	ds_bpermute_b32 v78, v204, v75
	v_pk_mul_f32 v[218:219], v[218:219], v[74:75]
	ds_bpermute_b32 v234, v204, v218
	v_mul_f32_e32 v81, v217, v216
	v_mov_b32_e32 v79, v215
	v_mov_b32_e32 v235, v214
	s_waitcnt lgkmcnt(1)
; #define LAS __attribute__((address_space(3)))
; __device__ __forceinline__ s16x4 ds_tr(LAS const unsigned char* p) { return __builtin_bit_cast(s16x4, __builtin_amdgcn_ds_read_tr16_b64_v4i16((LAS v4i16_t*)p)); }
; __device__ __forceinline__ bf16x8 cat8(s16x4 lo, s16x4 hi) { return (bf16x8){lo[0], lo[1], lo[2], lo[3], hi[0], hi[1], hi[2], hi[3]}; }
; __device__ __forceinline__ void sb_unit(LAS unsigned char* vs, const bf16* P, bf16* YB, int hd, int qb, int lane) {
;     ...
;         float e[16], tot[4], otot[4];
; #pragma unroll
;         for (int g = 0; g < 4; ++g) { e[4 * g + 3] = 1.f; e[4 * g + 2] = om[4 * g + 3]; e[4 * g + 1] = e[4 * g + 2] * om[4 * g + 2]; e[4 * g] = e[4 * g + 1] * om[4 * g + 1]; tot[g] = e[4 * g] * om[4 * g]; }
; #pragma unroll
;         for (int g = 0; g < 4; ++g) otot[g] = __shfl_xor(tot[g], 32);
;         float so[4], xe[4], base[4];
;         so[3] = 1.f; so[2] = tot[3]; so[1] = so[2] * tot[2]; so[0] = so[1] * tot[1];
;         xe[3] = 1.f; xe[2] = otot[3]; xe[1] = xe[2] * otot[2]; xe[0] = xe[1] * otot[1];
; #pragma unroll
;         for (int g = 0; g < 4; ++g) base[g] = R * so[g] * (hh == 0 ? xe[g] * otot[g] : xe[g]);
;         const float total = (so[0] * tot[0]) * (xe[0] * otot[0]);
;         float p[16];
; #pragma unroll
;         for (int r = 0; r < 16; ++r) p[r] = be[r] * ((r & 3) == 3 ? base[r >> 2] : base[r >> 2] * e[r]);
;         const bf16x8 pf0 = pack8(p[0], p[1], p[2], p[3], p[4], p[5], p[6], p[7]), pf1 = pack8(p[8], p[9], p[10], p[11], p[12], p[13], p[14], p[15]);
; #pragma unroll
;         for (int i = 0; i < 8; ++i) *(LAS u32x4*)(vs + (4 * i + (lane >> 4)) * KS_STRIDE + (lane & 15) * 16) = vr[i];
;         bf16x8 vf[4][2];
; #pragma unroll
;         for (int cb = 0; cb < 4; ++cb)
; #pragma unroll
;             for (int sp = 0; sp < 2; ++sp) { const int rlo = 16 * sp + 4 * hh + q4, rhi = rlo + 8; const int vcol = (32 * cb + 16 * g2 + 4 * p4) * 2;
;                 vf[cb][sp] = cat8(ds_tr(vs + rlo * KS_STRIDE + vcol), ds_tr(vs + rhi * KS_STRIDE + vcol)); }
; #pragma unroll
;         for (int sp = 0; sp < 2; ++sp)
; #pragma unroll
;             for (int cb = 0; cb < 4; ++cb) o[cb] = MFMA32(vf[cb][sp], sp ? pf1 : pf0, o[cb]);
;         R *= total;
;         if (__all(R == 0.f)) break;
; #pragma unroll
;         for (int ks = 0; ks < 8; ++ks) kf[ks] = kn[ks];
;     }
	v_pk_mul_f32 v[78:79], v[78:79], v[80:81]
	v_pk_mul_f32 v[236:237], v[218:219], v[218:219] op_sel:[0,1] op_sel_hi:[1,0]
	v_mul_f32_e32 v75, v190, v219
	s_waitcnt lgkmcnt(0)
	v_pk_mul_f32 v[218:219], v[78:79], v[234:235]
	ds_bpermute_b32 v234, v204, v219
	v_mov_b32_e32 v235, v236
	v_pk_mul_f32 v[206:207], v[206:207], v[214:215]
	v_mul_f32_e32 v194, v190, v178
	v_cndmask_b32_e64 v222, 1.0, v80, s[0:1]
	s_waitcnt lgkmcnt(0)
	v_pk_mul_f32 v[214:215], v[218:219], v[234:235]
	v_mul_f32_e32 v66, v190, v236
	v_cndmask_b32_e64 v178, v80, v78, s[0:1]
	v_cndmask_b32_e64 v80, v218, v214, s[0:1]
	v_mul_f32_e32 v66, v80, v66
	v_cndmask_b32_e64 v78, v78, v218, s[0:1]
	v_mov_b32_e32 v80, v79
	v_mul_f32_e32 v78, v78, v75
	v_pk_mul_f32 v[80:81], v[80:81], v[66:67] op_sel_hi:[1,0]
	v_mov_b32_e32 v75, v212
	v_pk_mul_f32 v[208:209], v[208:209], v[216:217]
	v_pk_mul_f32 v[80:81], v[206:207], v[80:81]
	v_mul_f32_e32 v206, v217, v66
	v_mov_b32_e32 v207, v66
	v_pk_mul_f32 v[74:75], v[74:75], v[78:79] op_sel_hi:[1,0]
	v_pk_mul_f32 v[206:207], v[208:209], v[206:207]
	v_pk_mul_f32 v[208:209], v[210:211], v[74:75]
	v_mul_f32_e32 v74, v70, v78
	v_mov_b32_e32 v75, v78
	v_pk_mul_f32 v[210:211], v[76:77], v[74:75]
	v_cvt_pk_bf16_f32 v74, v80, v81
	ds_read_b64_tr_b16 v[78:79], v198
	ds_read_b64_tr_b16 v[80:81], v198 offset:2176
	ds_read_b64_tr_b16 v[146:147], v198 offset:64
	ds_read_b64_tr_b16 v[150:151], v198 offset:128
	ds_read_b64_tr_b16 v[154:155], v198 offset:192
	ds_read_b64_tr_b16 v[148:149], v198 offset:2240
	ds_read_b64_tr_b16 v[152:153], v198 offset:2304
	ds_read_b64_tr_b16 v[156:157], v198 offset:2368
	v_pk_mul_f32 v[230:231], v[190:191], v[222:223]
	v_cvt_pk_bf16_f32 v75, v206, v207
	v_cvt_pk_bf16_f32 v76, v208, v209
	v_cvt_pk_bf16_f32 v77, v210, v211
	v_mul_f32_e32 v66, v178, v194
	v_mov_b32_e32 v70, v67
	v_mov_b32_e32 v232, v213
	s_waitcnt lgkmcnt(6)
	v_mfma_f32_32x32x16_bf16 v[2:17], v[78:81], v[74:77], v[2:17]
	v_mul_f32_e64 v78, v230, v224
	v_mul_f32_e64 v79, v230, v225
	v_mul_f32_e64 v68, v68, v70
	v_mul_f32_e64 v69, v69, v71
	v_mul_f32_e64 v70, v232, v66
	v_mul_f32_e64 v71, v233, v66
	v_pk_mul_f32 v[78:79], v[228:229], v[78:79]
	v_mul_f32_e32 v80, v230, v223
	v_mov_b32_e32 v227, v230
	v_mov_b32_e32 v81, v231
	s_waitcnt lgkmcnt(2)
	v_mfma_f32_32x32x16_bf16 v[18:33], v[146:149], v[74:77], v[18:33]
	v_mul_f32_e64 v158, v220, v72
	v_mul_f32_e64 v159, v221, v73
	v_mul_f32_e64 v68, v68, v70
	v_mul_f32_e64 v69, v69, v71
	v_mul_f32_e32 v70, v73, v66
	v_mov_b32_e32 v71, v66
	v_pk_mul_f32 v[70:71], v[158:159], v[70:71]
	v_cvt_pk_bf16_f32 v66, v68, v69
	v_cvt_pk_bf16_f32 v68, v78, v79
	s_waitcnt lgkmcnt(1)
	v_mfma_f32_32x32x16_bf16 v[34:49], v[150:153], v[74:77], v[34:49]
	v_mul_f32_e64 v78, v226, v80
	v_mul_f32_e64 v79, v227, v81
	v_cvt_pk_bf16_f32 v67, v70, v71
	ds_read_b64_tr_b16 v[70:71], v198 offset:4352
	ds_read_b64_tr_b16 v[72:73], v198 offset:6528
	v_cvt_pk_bf16_f32 v69, v78, v79
	s_waitcnt lgkmcnt(2)
	v_mfma_f32_32x32x16_bf16 v[50:65], v[154:157], v[74:77], v[50:65]
	ds_read_b64_tr_b16 v[74:75], v198 offset:4416
	ds_read_b64_tr_b16 v[78:79], v198 offset:4480
	ds_read_b64_tr_b16 v[146:147], v198 offset:4544
	ds_read_b64_tr_b16 v[76:77], v198 offset:6592
	ds_read_b64_tr_b16 v[80:81], v198 offset:6656
	ds_read_b64_tr_b16 v[148:149], v198 offset:6720
	s_waitcnt lgkmcnt(6)
	v_mfma_f32_32x32x16_bf16 v[2:17], v[70:73], v[66:69], v[2:17]
	v_mul_f32_e32 v70, v214, v215
	v_mul_f32_e32 v190, v190, v70
	v_cmp_eq_f32_e32 vcc, 0, v190
	s_cmp_lg_u64 vcc, exec
	s_cselect_b64 s[8:9], -1, 0
	s_cmp_eq_u64 vcc, exec
	s_waitcnt lgkmcnt(2)
	v_mfma_f32_32x32x16_bf16 v[18:33], v[74:77], v[66:69], v[18:33]
	s_waitcnt lgkmcnt(1)
	v_mfma_f32_32x32x16_bf16 v[34:49], v[78:81], v[66:69], v[34:49]
	s_waitcnt lgkmcnt(0)
	v_mfma_f32_32x32x16_bf16 v[50:65], v[146:149], v[66:69], v[50:65]
	s_branch .LBB0_541
